# prep: H0 = rmsnorm(x)*g through the pipelined hand-written row routine
# baseline (speedup 1.0000x reference)
; DI int obid() { int b = blockIdx.x; asm volatile("" : "+s"(b)); return b; }
; DI int ogrid() { int g = gridDim.x; asm volatile("" : "+s"(g)); return g; }
; DI int otid_w(int gw) { return (gw << 6) | olane(); }
; DI unsigned pk_bf16(float a, float b) { f32x2_t v = {a, b}; bf16x2_t r = __builtin_convertvector(v, bf16x2_t); return __builtin_bit_cast(unsigned, r); }
; DI float shx(float v, int mask) { const int l = olane(); return __builtin_bit_cast(float, __builtin_amdgcn_ds_bpermute(((l ^ mask) & 63) << 2, __builtin_bit_cast(int, v))); }
; DI void row_phase(const bf16_t* msrc, const float* xsrc, float* xdst, const float* g_post, const float* g_next, bf16_t* hdst, const int gw) {
;     constexpr int RB = 4;
;     const int tid = otid_w(gw); const int lane = tid & 63, w = tid >> 6;
;     const int wg = obid() * 8 + w, nw = ogrid() * 8;
;     for (int rowb = wg * RB; rowb < M_TOK; rowb += nw * RB) {
;         f32x4 xv[RB][4], mv[RB][4];
; #pragma unroll
;         for (int r = 0; r < RB; ++r)
; #pragma unroll
;             for (int j = 0; j < 4; ++j) xv[r][j] = *(const f32x4*)(xsrc + (size_t)(rowb + r) * DM + lane * 4 + 256 * j);
;     ...
;         if (hdst) {
;             float ss[RB];
; #pragma unroll
;             for (int r = 0; r < RB; ++r) { ss[r] = 0.f;
; #pragma unroll
;                 for (int j = 0; j < 4; ++j) ss[r] += xv[r][j][0] * xv[r][j][0] + xv[r][j][1] * xv[r][j][1] + xv[r][j][2] * xv[r][j][2] + xv[r][j][3] * xv[r][j][3]; }
; #pragma unroll
;             for (int o = 32; o >= 1; o >>= 1)
; #pragma unroll
;                 for (int r = 0; r < RB; ++r) ss[r] += shx(ss[r], o);
; #pragma unroll
;             for (int j = 0; j < 4; ++j) { const f32x4 g = *(const f32x4*)(g_next + lane * 4 + 256 * j);
; #pragma unroll
;                 for (int r = 0; r < RB; ++r) { const float r2 = rsqrtf(ss[r] * (1.f / DM) + EPS); const f32x4 hv = xv[r][j] * r2 * g;
;                     u32x2 o; o[0] = pk_bf16(hv[0], hv[1]); o[1] = pk_bf16(hv[2], hv[3]); *(u32x2*)(hdst + (size_t)(rowb + r) * DM + lane * 4 + 256 * j) = o; } }
.Lrow_r0:
	v_writelane_b32 v3, s4, 0
	v_writelane_b32 v3, s5, 1
	v_writelane_b32 v3, s6, 2
	v_writelane_b32 v3, s7, 3
	v_writelane_b32 v3, s8, 4
	v_writelane_b32 v3, s9, 5
	v_writelane_b32 v3, s10, 6
	v_writelane_b32 v3, s11, 7
	v_writelane_b32 v3, s12, 8
	v_writelane_b32 v3, s13, 9
	v_writelane_b32 v3, s14, 10
	v_writelane_b32 v3, s15, 11
	v_writelane_b32 v3, s16, 12
	v_writelane_b32 v3, s17, 13
	v_writelane_b32 v3, s18, 14
	v_writelane_b32 v3, s19, 15
	v_writelane_b32 v3, s20, 16
	v_writelane_b32 v3, s21, 17
	v_writelane_b32 v3, s22, 18
	v_writelane_b32 v3, s23, 19
	v_writelane_b32 v3, s24, 20
	v_writelane_b32 v3, s25, 21
	s_waitcnt vmcnt(0) lgkmcnt(0)
	v_mbcnt_lo_u32_b32 v0, -1, 0
	v_mbcnt_hi_u32_b32 v0, -1, v0
	v_lshlrev_b32_e32 v1, 5, v0
	v_lshlrev_b32_e32 v2, 4, v0
	s_lshr_b32 s4, s71, 6
	s_lshl_b32 s5, s2, 3
	s_add_i32 s5, s5, s4
	s_lshl_b32 s24, s5, 15
	s_lshl_b32 s25, s5, 14
	v_readlane_b32 s8, v254, 62
	v_readlane_b32 s9, v254, 63
	v_readlane_b32 s6, v255, 2
	v_readlane_b32 s7, v255, 3
	v_readlane_b32 s4, v255, 6
	v_readlane_b32 s16, v255, 10
	v_readlane_b32 s17, v255, 11
	s_mov_b32 s4, 0
	s_nop 1
	s_cmp_eq_u32 s4, 0
	s_cselect_b32 s6, s6, s8
	s_cselect_b32 s7, s7, s9
	s_add_u32 s6, s6, s24
	s_addc_u32 s7, s7, 0
	s_add_u32 s8, s8, s24
	s_addc_u32 s9, s9, 0
	s_add_u32 s10, s68, 0x10681000
	s_addc_u32 s11, s69, 0
	s_add_u32 s10, s10, s25
	s_addc_u32 s11, s11, 0
	s_add_u32 s12, s10, 0x2000000
	s_addc_u32 s13, s11, 0
	s_add_u32 s14, s68, 0x6681000
	s_addc_u32 s15, s69, 0
	s_add_u32 s14, s14, s25
	s_addc_u32 s15, s15, 0
	v_readlane_b32 s16, v255, 0
	v_readlane_b32 s17, v255, 1
	s_nop 3
	s_add_u32 s18, s16, 0x0
	s_addc_u32 s19, s17, 0
	global_load_dwordx4 v[56:59], v1, s[18:19] offset:0
	global_load_dwordx4 v[60:63], v1, s[18:19] offset:16
	global_load_dwordx4 v[64:67], v1, s[18:19] offset:2048
	global_load_dwordx4 v[68:71], v1, s[18:19] offset:2064
	global_load_dwordx4 v[96:99], v1, s[6:7] offset:0
	global_load_dwordx4 v[100:103], v1, s[6:7] offset:16
	global_load_dwordx4 v[104:107], v1, s[6:7] offset:2048
	global_load_dwordx4 v[108:111], v1, s[6:7] offset:2064
	s_add_u32 s6, s6, 0x1000
	s_addc_u32 s7, s7, 0
	s_add_u32 s10, s10, 0x800
	s_addc_u32 s11, s11, 0
	global_load_dwordx4 v[128:131], v1, s[6:7] offset:0
	global_load_dwordx4 v[132:135], v1, s[6:7] offset:16
	global_load_dwordx4 v[136:139], v1, s[6:7] offset:2048
	global_load_dwordx4 v[140:143], v1, s[6:7] offset:2064
	s_add_u32 s6, s6, 0x1000
	s_addc_u32 s7, s7, 0
	s_add_u32 s10, s10, 0x800
	s_addc_u32 s11, s11, 0
	global_load_dwordx4 v[160:163], v1, s[6:7] offset:0
	global_load_dwordx4 v[164:167], v1, s[6:7] offset:16
	global_load_dwordx4 v[168:171], v1, s[6:7] offset:2048
	global_load_dwordx4 v[172:175], v1, s[6:7] offset:2064
	s_add_u32 s6, s6, 0x1000
	s_addc_u32 s7, s7, 0
	s_add_u32 s10, s10, 0x800
	s_addc_u32 s11, s11, 0
	s_waitcnt vmcnt(8)
	v_mul_f32_e32 v224, v96, v96
	v_fmac_f32_e32 v224, v97, v97
	v_fmac_f32_e32 v224, v98, v98
	v_fmac_f32_e32 v224, v99, v99
	v_fmac_f32_e32 v224, v100, v100
	v_fmac_f32_e32 v224, v101, v101
	v_fmac_f32_e32 v224, v102, v102
	v_fmac_f32_e32 v224, v103, v103
	v_fmac_f32_e32 v224, v104, v104
	v_fmac_f32_e32 v224, v105, v105
	v_fmac_f32_e32 v224, v106, v106
	v_fmac_f32_e32 v224, v107, v107
	v_fmac_f32_e32 v224, v108, v108
	v_fmac_f32_e32 v224, v109, v109
	v_fmac_f32_e32 v224, v110, v110
	v_fmac_f32_e32 v224, v111, v111
	s_nop 1
	v_add_f32_dpp v224, v224, v224 quad_perm:[1,0,3,2] row_mask:0xf bank_mask:0xf
	s_nop 1
	v_add_f32_dpp v224, v224, v224 quad_perm:[2,3,0,1] row_mask:0xf bank_mask:0xf
	s_nop 1
	v_add_f32_dpp v224, v224, v224 row_ror:4 row_mask:0xf bank_mask:0xf
	s_nop 1
	v_add_f32_dpp v224, v224, v224 row_ror:8 row_mask:0xf bank_mask:0xf
	s_nop 1
	v_readlane_b32 s20, v224, 0
	v_readlane_b32 s21, v224, 16
	v_readlane_b32 s22, v224, 32
	v_readlane_b32 s23, v224, 48
	s_nop 1
	v_mov_b32_e32 v225, s20
	v_add_f32_e32 v225, s21, v225
	v_add_f32_e32 v225, s22, v225
	v_add_f32_e32 v225, s23, v225
	v_mov_b32_e32 v226, 0x358637bd
	v_fmac_f32_e32 v226, 0x3a800000, v225
	v_rsq_f32_e32 v226, v226
	s_nop 0
	v_mul_f32_e32 v208, v96, v226
	v_mul_f32_e32 v209, v97, v226
	v_mul_f32_e32 v210, v98, v226
	v_mul_f32_e32 v211, v99, v226
	v_mul_f32_e32 v212, v100, v226
	v_mul_f32_e32 v213, v101, v226
	v_mul_f32_e32 v214, v102, v226
	v_mul_f32_e32 v215, v103, v226
	v_mul_f32_e32 v216, v104, v226
	v_mul_f32_e32 v217, v105, v226
	v_mul_f32_e32 v218, v106, v226
	v_mul_f32_e32 v219, v107, v226
	v_mul_f32_e32 v220, v108, v226
	v_mul_f32_e32 v221, v109, v226
	v_mul_f32_e32 v222, v110, v226
	v_mul_f32_e32 v223, v111, v226
	v_mul_f32_e32 v208, v208, v56
	v_mul_f32_e32 v209, v209, v57
	v_mul_f32_e32 v210, v210, v58
	v_mul_f32_e32 v211, v211, v59
	v_mul_f32_e32 v212, v212, v60
	v_mul_f32_e32 v213, v213, v61
	v_mul_f32_e32 v214, v214, v62
	v_mul_f32_e32 v215, v215, v63
	v_mul_f32_e32 v216, v216, v64
	v_mul_f32_e32 v217, v217, v65
	v_mul_f32_e32 v218, v218, v66
	v_mul_f32_e32 v219, v219, v67
	v_mul_f32_e32 v220, v220, v68
	v_mul_f32_e32 v221, v221, v69
	v_mul_f32_e32 v222, v222, v70
	v_mul_f32_e32 v223, v223, v71
	v_cvt_pk_bf16_f32 v112, v208, v209
	v_cvt_pk_bf16_f32 v113, v210, v211
	v_cvt_pk_bf16_f32 v114, v212, v213
	v_cvt_pk_bf16_f32 v115, v214, v215
	v_cvt_pk_bf16_f32 v116, v216, v217
	v_cvt_pk_bf16_f32 v117, v218, v219
	v_cvt_pk_bf16_f32 v118, v220, v221
	v_cvt_pk_bf16_f32 v119, v222, v223
	global_store_dwordx4 v2, v[112:115], s[14:15]
	global_store_dwordx4 v2, v[116:119], s[14:15] offset:1024
	s_add_u32 s14, s14, 0x800
	s_addc_u32 s15, s15, 0
	global_load_dwordx4 v[96:99], v1, s[6:7] offset:0
	global_load_dwordx4 v[100:103], v1, s[6:7] offset:16
	global_load_dwordx4 v[104:107], v1, s[6:7] offset:2048
	global_load_dwordx4 v[108:111], v1, s[6:7] offset:2064
	s_add_u32 s6, s6, 0x1000
	s_addc_u32 s7, s7, 0
	s_add_u32 s10, s10, 0x800
	s_addc_u32 s11, s11, 0
	s_waitcnt vmcnt(10)
; DI unsigned pk_bf16(float a, float b) { f32x2_t v = {a, b}; bf16x2_t r = __builtin_convertvector(v, bf16x2_t); return __builtin_bit_cast(unsigned, r); }
; DI float shx(float v, int mask) { const int l = olane(); return __builtin_bit_cast(float, __builtin_amdgcn_ds_bpermute(((l ^ mask) & 63) << 2, __builtin_bit_cast(int, v))); }
; DI void row_phase(const bf16_t* msrc, const float* xsrc, float* xdst, const float* g_post, const float* g_next, bf16_t* hdst, const int gw) {
;     ...
;         if (hdst) {
;             float ss[RB];
; #pragma unroll
;             for (int r = 0; r < RB; ++r) { ss[r] = 0.f;
; #pragma unroll
;                 for (int j = 0; j < 4; ++j) ss[r] += xv[r][j][0] * xv[r][j][0] + xv[r][j][1] * xv[r][j][1] + xv[r][j][2] * xv[r][j][2] + xv[r][j][3] * xv[r][j][3]; }
; #pragma unroll
;             for (int o = 32; o >= 1; o >>= 1)
; #pragma unroll
;                 for (int r = 0; r < RB; ++r) ss[r] += shx(ss[r], o);
; #pragma unroll
;             for (int j = 0; j < 4; ++j) { const f32x4 g = *(const f32x4*)(g_next + lane * 4 + 256 * j);
; #pragma unroll
;                 for (int r = 0; r < RB; ++r) { const float r2 = rsqrtf(ss[r] * (1.f / DM) + EPS); const f32x4 hv = xv[r][j] * r2 * g;
;                     u32x2 o; o[0] = pk_bf16(hv[0], hv[1]); o[1] = pk_bf16(hv[2], hv[3]); *(u32x2*)(hdst + (size_t)(rowb + r) * DM + lane * 4 + 256 * j) = o; } }
	v_mul_f32_e32 v224, v128, v128
	v_fmac_f32_e32 v224, v129, v129
	v_fmac_f32_e32 v224, v130, v130
	v_fmac_f32_e32 v224, v131, v131
	v_fmac_f32_e32 v224, v132, v132
	v_fmac_f32_e32 v224, v133, v133
	v_fmac_f32_e32 v224, v134, v134
	v_fmac_f32_e32 v224, v135, v135
	v_fmac_f32_e32 v224, v136, v136
	v_fmac_f32_e32 v224, v137, v137
	v_fmac_f32_e32 v224, v138, v138
	v_fmac_f32_e32 v224, v139, v139
	v_fmac_f32_e32 v224, v140, v140
	v_fmac_f32_e32 v224, v141, v141
	v_fmac_f32_e32 v224, v142, v142
	v_fmac_f32_e32 v224, v143, v143
	s_nop 1
	v_add_f32_dpp v224, v224, v224 quad_perm:[1,0,3,2] row_mask:0xf bank_mask:0xf
	s_nop 1
	v_add_f32_dpp v224, v224, v224 quad_perm:[2,3,0,1] row_mask:0xf bank_mask:0xf
	s_nop 1
	v_add_f32_dpp v224, v224, v224 row_ror:4 row_mask:0xf bank_mask:0xf
	s_nop 1
	v_add_f32_dpp v224, v224, v224 row_ror:8 row_mask:0xf bank_mask:0xf
	s_nop 1
	v_readlane_b32 s20, v224, 0
	v_readlane_b32 s21, v224, 16
	v_readlane_b32 s22, v224, 32
	v_readlane_b32 s23, v224, 48
	s_nop 1
	v_mov_b32_e32 v225, s20
	v_add_f32_e32 v225, s21, v225
	v_add_f32_e32 v225, s22, v225
	v_add_f32_e32 v225, s23, v225
	v_mov_b32_e32 v226, 0x358637bd
	v_fmac_f32_e32 v226, 0x3a800000, v225
	v_rsq_f32_e32 v226, v226
	s_nop 0
	v_mul_f32_e32 v208, v128, v226
	v_mul_f32_e32 v209, v129, v226
	v_mul_f32_e32 v210, v130, v226
	v_mul_f32_e32 v211, v131, v226
	v_mul_f32_e32 v212, v132, v226
	v_mul_f32_e32 v213, v133, v226
	v_mul_f32_e32 v214, v134, v226
	v_mul_f32_e32 v215, v135, v226
	v_mul_f32_e32 v216, v136, v226
	v_mul_f32_e32 v217, v137, v226
	v_mul_f32_e32 v218, v138, v226
	v_mul_f32_e32 v219, v139, v226
	v_mul_f32_e32 v220, v140, v226
	v_mul_f32_e32 v221, v141, v226
	v_mul_f32_e32 v222, v142, v226
	v_mul_f32_e32 v223, v143, v226
	v_mul_f32_e32 v208, v208, v56
	v_mul_f32_e32 v209, v209, v57
	v_mul_f32_e32 v210, v210, v58
	v_mul_f32_e32 v211, v211, v59
	v_mul_f32_e32 v212, v212, v60
	v_mul_f32_e32 v213, v213, v61
	v_mul_f32_e32 v214, v214, v62
	v_mul_f32_e32 v215, v215, v63
	v_mul_f32_e32 v216, v216, v64
	v_mul_f32_e32 v217, v217, v65
	v_mul_f32_e32 v218, v218, v66
	v_mul_f32_e32 v219, v219, v67
	v_mul_f32_e32 v220, v220, v68
	v_mul_f32_e32 v221, v221, v69
	v_mul_f32_e32 v222, v222, v70
	v_mul_f32_e32 v223, v223, v71
	v_cvt_pk_bf16_f32 v144, v208, v209
	v_cvt_pk_bf16_f32 v145, v210, v211
	v_cvt_pk_bf16_f32 v146, v212, v213
	v_cvt_pk_bf16_f32 v147, v214, v215
	v_cvt_pk_bf16_f32 v148, v216, v217
	v_cvt_pk_bf16_f32 v149, v218, v219
	v_cvt_pk_bf16_f32 v150, v220, v221
	v_cvt_pk_bf16_f32 v151, v222, v223
	global_store_dwordx4 v2, v[144:147], s[14:15]
	global_store_dwordx4 v2, v[148:151], s[14:15] offset:1024
	s_add_u32 s14, s14, 0x800
	s_addc_u32 s15, s15, 0
	global_load_dwordx4 v[128:131], v1, s[6:7] offset:0
	global_load_dwordx4 v[132:135], v1, s[6:7] offset:16
	global_load_dwordx4 v[136:139], v1, s[6:7] offset:2048
	global_load_dwordx4 v[140:143], v1, s[6:7] offset:2064
	s_add_u32 s6, s6, 0x1000
	s_addc_u32 s7, s7, 0
	s_add_u32 s10, s10, 0x800
	s_addc_u32 s11, s11, 0
	s_waitcnt vmcnt(12)
	v_mul_f32_e32 v224, v160, v160
	v_fmac_f32_e32 v224, v161, v161
	v_fmac_f32_e32 v224, v162, v162
	v_fmac_f32_e32 v224, v163, v163
	v_fmac_f32_e32 v224, v164, v164
	v_fmac_f32_e32 v224, v165, v165
	v_fmac_f32_e32 v224, v166, v166
	v_fmac_f32_e32 v224, v167, v167
	v_fmac_f32_e32 v224, v168, v168
	v_fmac_f32_e32 v224, v169, v169
	v_fmac_f32_e32 v224, v170, v170
	v_fmac_f32_e32 v224, v171, v171
	v_fmac_f32_e32 v224, v172, v172
	v_fmac_f32_e32 v224, v173, v173
	v_fmac_f32_e32 v224, v174, v174
	v_fmac_f32_e32 v224, v175, v175
	s_nop 1
	v_add_f32_dpp v224, v224, v224 quad_perm:[1,0,3,2] row_mask:0xf bank_mask:0xf
	s_nop 1
	v_add_f32_dpp v224, v224, v224 quad_perm:[2,3,0,1] row_mask:0xf bank_mask:0xf
	s_nop 1
	v_add_f32_dpp v224, v224, v224 row_ror:4 row_mask:0xf bank_mask:0xf
	s_nop 1
	v_add_f32_dpp v224, v224, v224 row_ror:8 row_mask:0xf bank_mask:0xf
	s_nop 1
	v_readlane_b32 s20, v224, 0
	v_readlane_b32 s21, v224, 16
	v_readlane_b32 s22, v224, 32
	v_readlane_b32 s23, v224, 48
	s_nop 1
	v_mov_b32_e32 v225, s20
	v_add_f32_e32 v225, s21, v225
	v_add_f32_e32 v225, s22, v225
	v_add_f32_e32 v225, s23, v225
	v_mov_b32_e32 v226, 0x358637bd
	v_fmac_f32_e32 v226, 0x3a800000, v225
	v_rsq_f32_e32 v226, v226
	s_nop 0
	v_mul_f32_e32 v208, v160, v226
	v_mul_f32_e32 v209, v161, v226
	v_mul_f32_e32 v210, v162, v226
	v_mul_f32_e32 v211, v163, v226
	v_mul_f32_e32 v212, v164, v226
	v_mul_f32_e32 v213, v165, v226
	v_mul_f32_e32 v214, v166, v226
	v_mul_f32_e32 v215, v167, v226
	v_mul_f32_e32 v216, v168, v226
	v_mul_f32_e32 v217, v169, v226
	v_mul_f32_e32 v218, v170, v226
	v_mul_f32_e32 v219, v171, v226
	v_mul_f32_e32 v220, v172, v226
	v_mul_f32_e32 v221, v173, v226
	v_mul_f32_e32 v222, v174, v226
	v_mul_f32_e32 v223, v175, v226
	v_mul_f32_e32 v208, v208, v56
	v_mul_f32_e32 v209, v209, v57
	v_mul_f32_e32 v210, v210, v58
	v_mul_f32_e32 v211, v211, v59
	v_mul_f32_e32 v212, v212, v60
	v_mul_f32_e32 v213, v213, v61
	v_mul_f32_e32 v214, v214, v62
	v_mul_f32_e32 v215, v215, v63
	v_mul_f32_e32 v216, v216, v64
	v_mul_f32_e32 v217, v217, v65
	v_mul_f32_e32 v218, v218, v66
	v_mul_f32_e32 v219, v219, v67
	v_mul_f32_e32 v220, v220, v68
	v_mul_f32_e32 v221, v221, v69
	v_mul_f32_e32 v222, v222, v70
	v_mul_f32_e32 v223, v223, v71
	v_cvt_pk_bf16_f32 v176, v208, v209
	v_cvt_pk_bf16_f32 v177, v210, v211
	v_cvt_pk_bf16_f32 v178, v212, v213
	v_cvt_pk_bf16_f32 v179, v214, v215
	v_cvt_pk_bf16_f32 v180, v216, v217
	v_cvt_pk_bf16_f32 v181, v218, v219
	v_cvt_pk_bf16_f32 v182, v220, v221
	v_cvt_pk_bf16_f32 v183, v222, v223
	global_store_dwordx4 v2, v[176:179], s[14:15]
	global_store_dwordx4 v2, v[180:183], s[14:15] offset:1024
	s_add_u32 s14, s14, 0x800
	s_addc_u32 s15, s15, 0
	global_load_dwordx4 v[160:163], v1, s[6:7] offset:0
	global_load_dwordx4 v[164:167], v1, s[6:7] offset:16
	global_load_dwordx4 v[168:171], v1, s[6:7] offset:2048
	global_load_dwordx4 v[172:175], v1, s[6:7] offset:2064
	s_add_u32 s6, s6, 0x1000
	s_addc_u32 s7, s7, 0
	s_add_u32 s10, s10, 0x800
	s_addc_u32 s11, s11, 0
	s_waitcnt vmcnt(12)
; DI unsigned pk_bf16(float a, float b) { f32x2_t v = {a, b}; bf16x2_t r = __builtin_convertvector(v, bf16x2_t); return __builtin_bit_cast(unsigned, r); }
; DI float shx(float v, int mask) { const int l = olane(); return __builtin_bit_cast(float, __builtin_amdgcn_ds_bpermute(((l ^ mask) & 63) << 2, __builtin_bit_cast(int, v))); }
; DI void row_phase(const bf16_t* msrc, const float* xsrc, float* xdst, const float* g_post, const float* g_next, bf16_t* hdst, const int gw) {
;     ...
;         if (hdst) {
;             float ss[RB];
; #pragma unroll
;             for (int r = 0; r < RB; ++r) { ss[r] = 0.f;
; #pragma unroll
;                 for (int j = 0; j < 4; ++j) ss[r] += xv[r][j][0] * xv[r][j][0] + xv[r][j][1] * xv[r][j][1] + xv[r][j][2] * xv[r][j][2] + xv[r][j][3] * xv[r][j][3]; }
; #pragma unroll
;             for (int o = 32; o >= 1; o >>= 1)
; #pragma unroll
;                 for (int r = 0; r < RB; ++r) ss[r] += shx(ss[r], o);
; #pragma unroll
;             for (int j = 0; j < 4; ++j) { const f32x4 g = *(const f32x4*)(g_next + lane * 4 + 256 * j);
; #pragma unroll
;                 for (int r = 0; r < RB; ++r) { const float r2 = rsqrtf(ss[r] * (1.f / DM) + EPS); const f32x4 hv = xv[r][j] * r2 * g;
;                     u32x2 o; o[0] = pk_bf16(hv[0], hv[1]); o[1] = pk_bf16(hv[2], hv[3]); *(u32x2*)(hdst + (size_t)(rowb + r) * DM + lane * 4 + 256 * j) = o; } }
	v_mul_f32_e32 v224, v96, v96
	v_fmac_f32_e32 v224, v97, v97
	v_fmac_f32_e32 v224, v98, v98
	v_fmac_f32_e32 v224, v99, v99
	v_fmac_f32_e32 v224, v100, v100
	v_fmac_f32_e32 v224, v101, v101
	v_fmac_f32_e32 v224, v102, v102
	v_fmac_f32_e32 v224, v103, v103
	v_fmac_f32_e32 v224, v104, v104
	v_fmac_f32_e32 v224, v105, v105
	v_fmac_f32_e32 v224, v106, v106
	v_fmac_f32_e32 v224, v107, v107
	v_fmac_f32_e32 v224, v108, v108
	v_fmac_f32_e32 v224, v109, v109
	v_fmac_f32_e32 v224, v110, v110
	v_fmac_f32_e32 v224, v111, v111
	s_nop 1
	v_add_f32_dpp v224, v224, v224 quad_perm:[1,0,3,2] row_mask:0xf bank_mask:0xf
	s_nop 1
	v_add_f32_dpp v224, v224, v224 quad_perm:[2,3,0,1] row_mask:0xf bank_mask:0xf
	s_nop 1
	v_add_f32_dpp v224, v224, v224 row_ror:4 row_mask:0xf bank_mask:0xf
	s_nop 1
	v_add_f32_dpp v224, v224, v224 row_ror:8 row_mask:0xf bank_mask:0xf
	s_nop 1
	v_readlane_b32 s20, v224, 0
	v_readlane_b32 s21, v224, 16
	v_readlane_b32 s22, v224, 32
	v_readlane_b32 s23, v224, 48
	s_nop 1
	v_mov_b32_e32 v225, s20
	v_add_f32_e32 v225, s21, v225
	v_add_f32_e32 v225, s22, v225
	v_add_f32_e32 v225, s23, v225
	v_mov_b32_e32 v226, 0x358637bd
	v_fmac_f32_e32 v226, 0x3a800000, v225
	v_rsq_f32_e32 v226, v226
	s_nop 0
	v_mul_f32_e32 v208, v96, v226
	v_mul_f32_e32 v209, v97, v226
	v_mul_f32_e32 v210, v98, v226
	v_mul_f32_e32 v211, v99, v226
	v_mul_f32_e32 v212, v100, v226
	v_mul_f32_e32 v213, v101, v226
	v_mul_f32_e32 v214, v102, v226
	v_mul_f32_e32 v215, v103, v226
	v_mul_f32_e32 v216, v104, v226
	v_mul_f32_e32 v217, v105, v226
	v_mul_f32_e32 v218, v106, v226
	v_mul_f32_e32 v219, v107, v226
	v_mul_f32_e32 v220, v108, v226
	v_mul_f32_e32 v221, v109, v226
	v_mul_f32_e32 v222, v110, v226
	v_mul_f32_e32 v223, v111, v226
	v_mul_f32_e32 v208, v208, v56
	v_mul_f32_e32 v209, v209, v57
	v_mul_f32_e32 v210, v210, v58
	v_mul_f32_e32 v211, v211, v59
	v_mul_f32_e32 v212, v212, v60
	v_mul_f32_e32 v213, v213, v61
	v_mul_f32_e32 v214, v214, v62
	v_mul_f32_e32 v215, v215, v63
	v_mul_f32_e32 v216, v216, v64
	v_mul_f32_e32 v217, v217, v65
	v_mul_f32_e32 v218, v218, v66
	v_mul_f32_e32 v219, v219, v67
	v_mul_f32_e32 v220, v220, v68
	v_mul_f32_e32 v221, v221, v69
	v_mul_f32_e32 v222, v222, v70
	v_mul_f32_e32 v223, v223, v71
	v_cvt_pk_bf16_f32 v112, v208, v209
	v_cvt_pk_bf16_f32 v113, v210, v211
	v_cvt_pk_bf16_f32 v114, v212, v213
	v_cvt_pk_bf16_f32 v115, v214, v215
	v_cvt_pk_bf16_f32 v116, v216, v217
	v_cvt_pk_bf16_f32 v117, v218, v219
	v_cvt_pk_bf16_f32 v118, v220, v221
	v_cvt_pk_bf16_f32 v119, v222, v223
	global_store_dwordx4 v2, v[112:115], s[14:15]
	global_store_dwordx4 v2, v[116:119], s[14:15] offset:1024
	s_add_u32 s14, s14, 0x800
	s_addc_u32 s15, s15, 0
	global_load_dwordx4 v[96:99], v1, s[6:7] offset:0
	global_load_dwordx4 v[100:103], v1, s[6:7] offset:16
	global_load_dwordx4 v[104:107], v1, s[6:7] offset:2048
	global_load_dwordx4 v[108:111], v1, s[6:7] offset:2064
	s_add_u32 s6, s6, 0x1000
	s_addc_u32 s7, s7, 0
	s_add_u32 s10, s10, 0x800
	s_addc_u32 s11, s11, 0
	s_waitcnt vmcnt(12)
	v_mul_f32_e32 v224, v128, v128
	v_fmac_f32_e32 v224, v129, v129
	v_fmac_f32_e32 v224, v130, v130
	v_fmac_f32_e32 v224, v131, v131
	v_fmac_f32_e32 v224, v132, v132
	v_fmac_f32_e32 v224, v133, v133
	v_fmac_f32_e32 v224, v134, v134
	v_fmac_f32_e32 v224, v135, v135
	v_fmac_f32_e32 v224, v136, v136
	v_fmac_f32_e32 v224, v137, v137
	v_fmac_f32_e32 v224, v138, v138
	v_fmac_f32_e32 v224, v139, v139
	v_fmac_f32_e32 v224, v140, v140
	v_fmac_f32_e32 v224, v141, v141
	v_fmac_f32_e32 v224, v142, v142
	v_fmac_f32_e32 v224, v143, v143
	s_nop 1
	v_add_f32_dpp v224, v224, v224 quad_perm:[1,0,3,2] row_mask:0xf bank_mask:0xf
	s_nop 1
	v_add_f32_dpp v224, v224, v224 quad_perm:[2,3,0,1] row_mask:0xf bank_mask:0xf
	s_nop 1
	v_add_f32_dpp v224, v224, v224 row_ror:4 row_mask:0xf bank_mask:0xf
	s_nop 1
	v_add_f32_dpp v224, v224, v224 row_ror:8 row_mask:0xf bank_mask:0xf
	s_nop 1
	v_readlane_b32 s20, v224, 0
	v_readlane_b32 s21, v224, 16
	v_readlane_b32 s22, v224, 32
	v_readlane_b32 s23, v224, 48
	s_nop 1
	v_mov_b32_e32 v225, s20
	v_add_f32_e32 v225, s21, v225
	v_add_f32_e32 v225, s22, v225
	v_add_f32_e32 v225, s23, v225
	v_mov_b32_e32 v226, 0x358637bd
	v_fmac_f32_e32 v226, 0x3a800000, v225
	v_rsq_f32_e32 v226, v226
	s_nop 0
	v_mul_f32_e32 v208, v128, v226
	v_mul_f32_e32 v209, v129, v226
	v_mul_f32_e32 v210, v130, v226
	v_mul_f32_e32 v211, v131, v226
	v_mul_f32_e32 v212, v132, v226
	v_mul_f32_e32 v213, v133, v226
	v_mul_f32_e32 v214, v134, v226
	v_mul_f32_e32 v215, v135, v226
	v_mul_f32_e32 v216, v136, v226
	v_mul_f32_e32 v217, v137, v226
	v_mul_f32_e32 v218, v138, v226
	v_mul_f32_e32 v219, v139, v226
	v_mul_f32_e32 v220, v140, v226
	v_mul_f32_e32 v221, v141, v226
	v_mul_f32_e32 v222, v142, v226
	v_mul_f32_e32 v223, v143, v226
	v_mul_f32_e32 v208, v208, v56
	v_mul_f32_e32 v209, v209, v57
	v_mul_f32_e32 v210, v210, v58
	v_mul_f32_e32 v211, v211, v59
	v_mul_f32_e32 v212, v212, v60
	v_mul_f32_e32 v213, v213, v61
	v_mul_f32_e32 v214, v214, v62
	v_mul_f32_e32 v215, v215, v63
	v_mul_f32_e32 v216, v216, v64
	v_mul_f32_e32 v217, v217, v65
	v_mul_f32_e32 v218, v218, v66
	v_mul_f32_e32 v219, v219, v67
	v_mul_f32_e32 v220, v220, v68
	v_mul_f32_e32 v221, v221, v69
	v_mul_f32_e32 v222, v222, v70
	v_mul_f32_e32 v223, v223, v71
	v_cvt_pk_bf16_f32 v144, v208, v209
	v_cvt_pk_bf16_f32 v145, v210, v211
	v_cvt_pk_bf16_f32 v146, v212, v213
	v_cvt_pk_bf16_f32 v147, v214, v215
	v_cvt_pk_bf16_f32 v148, v216, v217
	v_cvt_pk_bf16_f32 v149, v218, v219
	v_cvt_pk_bf16_f32 v150, v220, v221
	v_cvt_pk_bf16_f32 v151, v222, v223
	global_store_dwordx4 v2, v[144:147], s[14:15]
	global_store_dwordx4 v2, v[148:151], s[14:15] offset:1024
	s_add_u32 s14, s14, 0x800
	s_addc_u32 s15, s15, 0
	global_load_dwordx4 v[128:131], v1, s[6:7] offset:0
	global_load_dwordx4 v[132:135], v1, s[6:7] offset:16
	global_load_dwordx4 v[136:139], v1, s[6:7] offset:2048
	global_load_dwordx4 v[140:143], v1, s[6:7] offset:2064
	s_add_u32 s6, s6, 0x1000
	s_addc_u32 s7, s7, 0
	s_add_u32 s10, s10, 0x800
	s_addc_u32 s11, s11, 0
	s_waitcnt vmcnt(12)
; DI unsigned pk_bf16(float a, float b) { f32x2_t v = {a, b}; bf16x2_t r = __builtin_convertvector(v, bf16x2_t); return __builtin_bit_cast(unsigned, r); }
; DI float shx(float v, int mask) { const int l = olane(); return __builtin_bit_cast(float, __builtin_amdgcn_ds_bpermute(((l ^ mask) & 63) << 2, __builtin_bit_cast(int, v))); }
; DI void row_phase(const bf16_t* msrc, const float* xsrc, float* xdst, const float* g_post, const float* g_next, bf16_t* hdst, const int gw) {
;     ...
;         if (hdst) {
;             float ss[RB];
; #pragma unroll
;             for (int r = 0; r < RB; ++r) { ss[r] = 0.f;
; #pragma unroll
;                 for (int j = 0; j < 4; ++j) ss[r] += xv[r][j][0] * xv[r][j][0] + xv[r][j][1] * xv[r][j][1] + xv[r][j][2] * xv[r][j][2] + xv[r][j][3] * xv[r][j][3]; }
; #pragma unroll
;             for (int o = 32; o >= 1; o >>= 1)
; #pragma unroll
;                 for (int r = 0; r < RB; ++r) ss[r] += shx(ss[r], o);
; #pragma unroll
;             for (int j = 0; j < 4; ++j) { const f32x4 g = *(const f32x4*)(g_next + lane * 4 + 256 * j);
; #pragma unroll
;                 for (int r = 0; r < RB; ++r) { const float r2 = rsqrtf(ss[r] * (1.f / DM) + EPS); const f32x4 hv = xv[r][j] * r2 * g;
;                     u32x2 o; o[0] = pk_bf16(hv[0], hv[1]); o[1] = pk_bf16(hv[2], hv[3]); *(u32x2*)(hdst + (size_t)(rowb + r) * DM + lane * 4 + 256 * j) = o; } }
	v_mul_f32_e32 v224, v160, v160
	v_fmac_f32_e32 v224, v161, v161
	v_fmac_f32_e32 v224, v162, v162
	v_fmac_f32_e32 v224, v163, v163
	v_fmac_f32_e32 v224, v164, v164
	v_fmac_f32_e32 v224, v165, v165
	v_fmac_f32_e32 v224, v166, v166
	v_fmac_f32_e32 v224, v167, v167
	v_fmac_f32_e32 v224, v168, v168
	v_fmac_f32_e32 v224, v169, v169
	v_fmac_f32_e32 v224, v170, v170
	v_fmac_f32_e32 v224, v171, v171
	v_fmac_f32_e32 v224, v172, v172
	v_fmac_f32_e32 v224, v173, v173
	v_fmac_f32_e32 v224, v174, v174
	v_fmac_f32_e32 v224, v175, v175
	s_nop 1
	v_add_f32_dpp v224, v224, v224 quad_perm:[1,0,3,2] row_mask:0xf bank_mask:0xf
	s_nop 1
	v_add_f32_dpp v224, v224, v224 quad_perm:[2,3,0,1] row_mask:0xf bank_mask:0xf
	s_nop 1
	v_add_f32_dpp v224, v224, v224 row_ror:4 row_mask:0xf bank_mask:0xf
	s_nop 1
	v_add_f32_dpp v224, v224, v224 row_ror:8 row_mask:0xf bank_mask:0xf
	s_nop 1
	v_readlane_b32 s20, v224, 0
	v_readlane_b32 s21, v224, 16
	v_readlane_b32 s22, v224, 32
	v_readlane_b32 s23, v224, 48
	s_nop 1
	v_mov_b32_e32 v225, s20
	v_add_f32_e32 v225, s21, v225
	v_add_f32_e32 v225, s22, v225
	v_add_f32_e32 v225, s23, v225
	v_mov_b32_e32 v226, 0x358637bd
	v_fmac_f32_e32 v226, 0x3a800000, v225
	v_rsq_f32_e32 v226, v226
	s_nop 0
	v_mul_f32_e32 v208, v160, v226
	v_mul_f32_e32 v209, v161, v226
	v_mul_f32_e32 v210, v162, v226
	v_mul_f32_e32 v211, v163, v226
	v_mul_f32_e32 v212, v164, v226
	v_mul_f32_e32 v213, v165, v226
	v_mul_f32_e32 v214, v166, v226
	v_mul_f32_e32 v215, v167, v226
	v_mul_f32_e32 v216, v168, v226
	v_mul_f32_e32 v217, v169, v226
	v_mul_f32_e32 v218, v170, v226
	v_mul_f32_e32 v219, v171, v226
	v_mul_f32_e32 v220, v172, v226
	v_mul_f32_e32 v221, v173, v226
	v_mul_f32_e32 v222, v174, v226
	v_mul_f32_e32 v223, v175, v226
	v_mul_f32_e32 v208, v208, v56
	v_mul_f32_e32 v209, v209, v57
	v_mul_f32_e32 v210, v210, v58
	v_mul_f32_e32 v211, v211, v59
	v_mul_f32_e32 v212, v212, v60
	v_mul_f32_e32 v213, v213, v61
	v_mul_f32_e32 v214, v214, v62
	v_mul_f32_e32 v215, v215, v63
	v_mul_f32_e32 v216, v216, v64
	v_mul_f32_e32 v217, v217, v65
	v_mul_f32_e32 v218, v218, v66
	v_mul_f32_e32 v219, v219, v67
	v_mul_f32_e32 v220, v220, v68
	v_mul_f32_e32 v221, v221, v69
	v_mul_f32_e32 v222, v222, v70
	v_mul_f32_e32 v223, v223, v71
	v_cvt_pk_bf16_f32 v176, v208, v209
	v_cvt_pk_bf16_f32 v177, v210, v211
	v_cvt_pk_bf16_f32 v178, v212, v213
	v_cvt_pk_bf16_f32 v179, v214, v215
	v_cvt_pk_bf16_f32 v180, v216, v217
	v_cvt_pk_bf16_f32 v181, v218, v219
	v_cvt_pk_bf16_f32 v182, v220, v221
	v_cvt_pk_bf16_f32 v183, v222, v223
	global_store_dwordx4 v2, v[176:179], s[14:15]
	global_store_dwordx4 v2, v[180:183], s[14:15] offset:1024
	s_add_u32 s14, s14, 0x800
	s_addc_u32 s15, s15, 0
	s_waitcnt vmcnt(8)
	v_mul_f32_e32 v224, v96, v96
	v_fmac_f32_e32 v224, v97, v97
	v_fmac_f32_e32 v224, v98, v98
	v_fmac_f32_e32 v224, v99, v99
	v_fmac_f32_e32 v224, v100, v100
	v_fmac_f32_e32 v224, v101, v101
	v_fmac_f32_e32 v224, v102, v102
	v_fmac_f32_e32 v224, v103, v103
	v_fmac_f32_e32 v224, v104, v104
	v_fmac_f32_e32 v224, v105, v105
	v_fmac_f32_e32 v224, v106, v106
	v_fmac_f32_e32 v224, v107, v107
	v_fmac_f32_e32 v224, v108, v108
	v_fmac_f32_e32 v224, v109, v109
	v_fmac_f32_e32 v224, v110, v110
	v_fmac_f32_e32 v224, v111, v111
	s_nop 1
	v_add_f32_dpp v224, v224, v224 quad_perm:[1,0,3,2] row_mask:0xf bank_mask:0xf
	s_nop 1
	v_add_f32_dpp v224, v224, v224 quad_perm:[2,3,0,1] row_mask:0xf bank_mask:0xf
	s_nop 1
	v_add_f32_dpp v224, v224, v224 row_ror:4 row_mask:0xf bank_mask:0xf
	s_nop 1
	v_add_f32_dpp v224, v224, v224 row_ror:8 row_mask:0xf bank_mask:0xf
	s_nop 1
	v_readlane_b32 s20, v224, 0
	v_readlane_b32 s21, v224, 16
	v_readlane_b32 s22, v224, 32
	v_readlane_b32 s23, v224, 48
	s_nop 1
	v_mov_b32_e32 v225, s20
	v_add_f32_e32 v225, s21, v225
	v_add_f32_e32 v225, s22, v225
	v_add_f32_e32 v225, s23, v225
	v_mov_b32_e32 v226, 0x358637bd
	v_fmac_f32_e32 v226, 0x3a800000, v225
	v_rsq_f32_e32 v226, v226
	s_nop 0
	v_mul_f32_e32 v208, v96, v226
	v_mul_f32_e32 v209, v97, v226
	v_mul_f32_e32 v210, v98, v226
	v_mul_f32_e32 v211, v99, v226
	v_mul_f32_e32 v212, v100, v226
	v_mul_f32_e32 v213, v101, v226
	v_mul_f32_e32 v214, v102, v226
	v_mul_f32_e32 v215, v103, v226
	v_mul_f32_e32 v216, v104, v226
	v_mul_f32_e32 v217, v105, v226
	v_mul_f32_e32 v218, v106, v226
	v_mul_f32_e32 v219, v107, v226
	v_mul_f32_e32 v220, v108, v226
	v_mul_f32_e32 v221, v109, v226
	v_mul_f32_e32 v222, v110, v226
	v_mul_f32_e32 v223, v111, v226
	v_mul_f32_e32 v208, v208, v56
	v_mul_f32_e32 v209, v209, v57
	v_mul_f32_e32 v210, v210, v58
	v_mul_f32_e32 v211, v211, v59
	v_mul_f32_e32 v212, v212, v60
	v_mul_f32_e32 v213, v213, v61
	v_mul_f32_e32 v214, v214, v62
	v_mul_f32_e32 v215, v215, v63
	v_mul_f32_e32 v216, v216, v64
	v_mul_f32_e32 v217, v217, v65
	v_mul_f32_e32 v218, v218, v66
	v_mul_f32_e32 v219, v219, v67
	v_mul_f32_e32 v220, v220, v68
	v_mul_f32_e32 v221, v221, v69
	v_mul_f32_e32 v222, v222, v70
	v_mul_f32_e32 v223, v223, v71
	v_cvt_pk_bf16_f32 v112, v208, v209
	v_cvt_pk_bf16_f32 v113, v210, v211
	v_cvt_pk_bf16_f32 v114, v212, v213
	v_cvt_pk_bf16_f32 v115, v214, v215
	v_cvt_pk_bf16_f32 v116, v216, v217
	v_cvt_pk_bf16_f32 v117, v218, v219
	v_cvt_pk_bf16_f32 v118, v220, v221
	v_cvt_pk_bf16_f32 v119, v222, v223
	global_store_dwordx4 v2, v[112:115], s[14:15]
	global_store_dwordx4 v2, v[116:119], s[14:15] offset:1024
	s_add_u32 s14, s14, 0x800
	s_addc_u32 s15, s15, 0
	s_waitcnt vmcnt(4)
; DI unsigned pk_bf16(float a, float b) { f32x2_t v = {a, b}; bf16x2_t r = __builtin_convertvector(v, bf16x2_t); return __builtin_bit_cast(unsigned, r); }
; DI float shx(float v, int mask) { const int l = olane(); return __builtin_bit_cast(float, __builtin_amdgcn_ds_bpermute(((l ^ mask) & 63) << 2, __builtin_bit_cast(int, v))); }
; DI void row_phase(const bf16_t* msrc, const float* xsrc, float* xdst, const float* g_post, const float* g_next, bf16_t* hdst, const int gw) {
;     ...
;         if (hdst) {
;             float ss[RB];
; #pragma unroll
;             for (int r = 0; r < RB; ++r) { ss[r] = 0.f;
; #pragma unroll
;                 for (int j = 0; j < 4; ++j) ss[r] += xv[r][j][0] * xv[r][j][0] + xv[r][j][1] * xv[r][j][1] + xv[r][j][2] * xv[r][j][2] + xv[r][j][3] * xv[r][j][3]; }
; #pragma unroll
;             for (int o = 32; o >= 1; o >>= 1)
; #pragma unroll
;                 for (int r = 0; r < RB; ++r) ss[r] += shx(ss[r], o);
; #pragma unroll
;             for (int j = 0; j < 4; ++j) { const f32x4 g = *(const f32x4*)(g_next + lane * 4 + 256 * j);
; #pragma unroll
;                 for (int r = 0; r < RB; ++r) { const float r2 = rsqrtf(ss[r] * (1.f / DM) + EPS); const f32x4 hv = xv[r][j] * r2 * g;
;                     u32x2 o; o[0] = pk_bf16(hv[0], hv[1]); o[1] = pk_bf16(hv[2], hv[3]); *(u32x2*)(hdst + (size_t)(rowb + r) * DM + lane * 4 + 256 * j) = o; } }
	v_mul_f32_e32 v224, v128, v128
	v_fmac_f32_e32 v224, v129, v129
	v_fmac_f32_e32 v224, v130, v130
	v_fmac_f32_e32 v224, v131, v131
	v_fmac_f32_e32 v224, v132, v132
	v_fmac_f32_e32 v224, v133, v133
	v_fmac_f32_e32 v224, v134, v134
	v_fmac_f32_e32 v224, v135, v135
	v_fmac_f32_e32 v224, v136, v136
	v_fmac_f32_e32 v224, v137, v137
	v_fmac_f32_e32 v224, v138, v138
	v_fmac_f32_e32 v224, v139, v139
	v_fmac_f32_e32 v224, v140, v140
	v_fmac_f32_e32 v224, v141, v141
	v_fmac_f32_e32 v224, v142, v142
	v_fmac_f32_e32 v224, v143, v143
	s_nop 1
	v_add_f32_dpp v224, v224, v224 quad_perm:[1,0,3,2] row_mask:0xf bank_mask:0xf
	s_nop 1
	v_add_f32_dpp v224, v224, v224 quad_perm:[2,3,0,1] row_mask:0xf bank_mask:0xf
	s_nop 1
	v_add_f32_dpp v224, v224, v224 row_ror:4 row_mask:0xf bank_mask:0xf
	s_nop 1
	v_add_f32_dpp v224, v224, v224 row_ror:8 row_mask:0xf bank_mask:0xf
	s_nop 1
	v_readlane_b32 s20, v224, 0
	v_readlane_b32 s21, v224, 16
	v_readlane_b32 s22, v224, 32
	v_readlane_b32 s23, v224, 48
	s_nop 1
	v_mov_b32_e32 v225, s20
	v_add_f32_e32 v225, s21, v225
	v_add_f32_e32 v225, s22, v225
	v_add_f32_e32 v225, s23, v225
	v_mov_b32_e32 v226, 0x358637bd
	v_fmac_f32_e32 v226, 0x3a800000, v225
	v_rsq_f32_e32 v226, v226
	s_nop 0
	v_mul_f32_e32 v208, v128, v226
	v_mul_f32_e32 v209, v129, v226
	v_mul_f32_e32 v210, v130, v226
	v_mul_f32_e32 v211, v131, v226
	v_mul_f32_e32 v212, v132, v226
	v_mul_f32_e32 v213, v133, v226
	v_mul_f32_e32 v214, v134, v226
	v_mul_f32_e32 v215, v135, v226
	v_mul_f32_e32 v216, v136, v226
	v_mul_f32_e32 v217, v137, v226
	v_mul_f32_e32 v218, v138, v226
	v_mul_f32_e32 v219, v139, v226
	v_mul_f32_e32 v220, v140, v226
	v_mul_f32_e32 v221, v141, v226
	v_mul_f32_e32 v222, v142, v226
	v_mul_f32_e32 v223, v143, v226
	v_mul_f32_e32 v208, v208, v56
	v_mul_f32_e32 v209, v209, v57
	v_mul_f32_e32 v210, v210, v58
	v_mul_f32_e32 v211, v211, v59
	v_mul_f32_e32 v212, v212, v60
	v_mul_f32_e32 v213, v213, v61
	v_mul_f32_e32 v214, v214, v62
	v_mul_f32_e32 v215, v215, v63
	v_mul_f32_e32 v216, v216, v64
	v_mul_f32_e32 v217, v217, v65
	v_mul_f32_e32 v218, v218, v66
	v_mul_f32_e32 v219, v219, v67
	v_mul_f32_e32 v220, v220, v68
	v_mul_f32_e32 v221, v221, v69
	v_mul_f32_e32 v222, v222, v70
	v_mul_f32_e32 v223, v223, v71
	v_cvt_pk_bf16_f32 v144, v208, v209
	v_cvt_pk_bf16_f32 v145, v210, v211
	v_cvt_pk_bf16_f32 v146, v212, v213
	v_cvt_pk_bf16_f32 v147, v214, v215
	v_cvt_pk_bf16_f32 v148, v216, v217
	v_cvt_pk_bf16_f32 v149, v218, v219
	v_cvt_pk_bf16_f32 v150, v220, v221
	v_cvt_pk_bf16_f32 v151, v222, v223
	global_store_dwordx4 v2, v[144:147], s[14:15]
	global_store_dwordx4 v2, v[148:151], s[14:15] offset:1024
	s_add_u32 s14, s14, 0x800
	s_addc_u32 s15, s15, 0
	v_readlane_b32 s4, v3, 0
	v_readlane_b32 s5, v3, 1
	v_readlane_b32 s6, v3, 2
	v_readlane_b32 s7, v3, 3
	v_readlane_b32 s8, v3, 4
	v_readlane_b32 s9, v3, 5
	v_readlane_b32 s10, v3, 6
	v_readlane_b32 s11, v3, 7
	v_readlane_b32 s12, v3, 8
	v_readlane_b32 s13, v3, 9
	v_readlane_b32 s14, v3, 10
	v_readlane_b32 s15, v3, 11
	v_readlane_b32 s16, v3, 12
	v_readlane_b32 s17, v3, 13
	v_readlane_b32 s18, v3, 14
	v_readlane_b32 s19, v3, 15
	v_readlane_b32 s20, v3, 16
	v_readlane_b32 s21, v3, 17
	v_readlane_b32 s22, v3, 18
	v_readlane_b32 s23, v3, 19
	v_readlane_b32 s24, v3, 20
	v_readlane_b32 s25, v3, 21
	s_mov_b32 s6, 0x358637bd
	s_mov_b32 s16, 0x358637bd
	s_branch .LBB0_493
.LBB0_490:
	s_branch .Lrow_r0
.LBB0_493:
	s_or_b64 exec, exec, s[6:7]
	s_add_i32 s36, s36, 1
	s_cmp_ge_i32 s36, s31
	s_mov_b64 s[4:5], -1
	s_cbranch_scc0 .LBB0_494
	s_getpc_b64 s[98:99]
